# P7->P8 barrier split: lru_x-done arrival issued from inside P7's second unit, checked at P8 start; xa_q-done arrival checked after the conv
# speedup vs baseline: 1.0039x; 1.0039x over previous
.Ldw_done_p7:
.Ldw_skip_p7:
	s_cmp_lg_u32 s100, 0
	s_cbranch_scc1 .Lp7a_skip
	s_cmp_lg_u32 s69, 2
	s_cbranch_scc1 .Lp7a_skip
	s_mov_b32 s100, 2
	s_cmp_eq_u64 s[92:93], 0
	s_cbranch_scc1 .Lp7a_skip
	s_mov_b64 exec, 1
	v_mov_b32_e32 v216, 0x22000
	ds_read_b32 v217, v216
	s_lshl_b32 s101, s87, 8
	s_add_i32 s101, s101, 0x2b5d040
	v_mov_b32_e32 v216, s101
	v_mov_b32_e32 v218, 1
	global_atomic_add v219, v216, v218, s[88:89] sc0
	s_waitcnt vmcnt(0) lgkmcnt(0)
	v_add_u32_e32 v219, 1, v219
	v_cmp_eq_u32_e32 vcc, v219, v217
	s_cbranch_vccz .Lp7a_end
	buffer_wbl2 sc1
	s_waitcnt vmcnt(0)
	v_mov_b32_e32 v216, 0x2b5d044
	global_atomic_add v216, v218, s[88:89]
.Lp7a_end:
	s_mov_b64 exec, -1

.LBB0_1064:
	s_waitcnt vmcnt(0)
	s_waitcnt lgkmcnt(0)
	s_barrier
	s_and_saveexec_b64 s[10:11], s[92:93]
	s_cbranch_execz .LBB0_1116
	v_mov_b32_e32 v2, 0x22000
	ds_read_b64 v[4:5], v2
	s_lshl_b32 s0, s87, 8
	s_add_i32 s0, s0, 0x2b5d048
	v_mov_b32_e32 v2, s0
	v_mov_b32_e32 v3, 1
	global_atomic_add v6, v2, v3, s[88:89] sc0
	s_waitcnt vmcnt(0) lgkmcnt(0)
	v_add_u32_e32 v6, 1, v6
	v_cmp_eq_u32_e32 vcc, v6, v4
	s_cbranch_vccz .Lp8s_notlast
	buffer_wbl2 sc1
	s_waitcnt vmcnt(0)
	v_mov_b32_e32 v2, 0x2b5d04c
	global_atomic_add v2, v3, s[88:89]
.Lp8s_notlast:
	v_mov_b32_e32 v2, 0x2b5d044
	s_mov_b32 s1, 0x100000
.Lp8s_poll:
	global_load_dword v3, v2, s[88:89] sc1
	s_waitcnt vmcnt(0)
	v_cmp_ge_u32_e32 vcc, v3, v5
	s_cbranch_vccnz .Lp8s_done
	s_sleep 1
	s_sub_u32 s1, s1, 1
	s_cmp_lg_u32 s1, 0
	s_cbranch_scc1 .Lp8s_poll
.Lp8s_done:
	buffer_inv sc1
	s_waitcnt vmcnt(0)
.LBB0_1116:
	s_or_b64 exec, exec, s[10:11]
	s_waitcnt lgkmcnt(0)
	v_mov_b32_e32 v2, v0
	s_barrier
	s_mov_b32 s0, 0x20000
	v_add_u32_e32 v142, s84, v2
	v_cmp_gt_i32_e32 vcc, s0, v142
	s_and_saveexec_b64 s[18:19], vcc
	s_cbranch_execz .LBB0_1125
	s_load_dwordx2 s[0:1], s[96:97], 0xe8
	s_load_dwordx4 s[12:15], s[96:97], 0x28
	v_lshlrev_b32_e32 v2, 3, v2
	v_lshl_add_u32 v143, s2, 12, v2
	s_mov_b64 s[40:41], 0
	s_waitcnt lgkmcnt(0)
	s_add_u32 s20, s0, 0x2e00000
	s_addc_u32 s21, s1, 0
	s_add_u32 s22, s0, 0x8e00000
	s_addc_u32 s23, s1, 0
	s_lshl_b32 s3, s90, 12
	v_mov_b32_e32 v103, 0
	s_mov_b64 s[42:43], 0x1000
	s_mov_b64 s[44:45], 0x2000
	s_movk_i32 s4, 0x2000
	s_mov_b64 s[46:47], 0x3000
	s_movk_i32 s5, 0x3000
	s_mov_b32 s6, 0x1ffff
	s_branch .LBB0_1119

.Lp8c_end:
	v_mov_b32_e32 v2, 0x22004
	ds_read_b32 v4, v2
	v_mov_b32_e32 v2, 0x2b5d04c
	s_mov_b32 s1, 0x100000
	s_waitcnt lgkmcnt(0)

.Lp8c_out:
	s_or_b64 exec, exec, s[100:101]
	s_barrier
	v_readlane_b32 s0, v254, 5
	v_readlane_b32 s1, v254, 6
	s_and_b64 vcc, exec, s[0:1]
	s_cbranch_vccnz .LBB0_1173
	s_load_dwordx2 s[12:13], s[96:97], 0xe8
	v_readlane_b32 s0, v254, 9
	v_readlane_b32 s1, v254, 10
	s_ashr_i32 s1, s0, 31
	v_mov_b32_e32 v30, v0
	s_lshl_b64 s[18:19], s[0:1], 19
	s_lshl_b32 s3, s37, 9
	s_ashr_i32 s20, s2, 7
	v_bfe_i32 v4, v30, 27, 1
	s_or_b32 s18, s18, s3
	v_lshlrev_b32_e32 v2, 4, v30
	v_lshrrev_b32_e32 v4, 22, v4
	s_waitcnt lgkmcnt(0)
	s_add_u32 s0, s12, s18
	v_add_u32_e32 v4, v2, v4
	s_addc_u32 s1, s13, s19
	v_and_b32_e32 v4, 0xfffffc00, v4
	s_add_u32 s4, s0, 0x4e00000
	v_sub_u32_e32 v2, v2, v4
	s_addc_u32 s5, s1, 0
	s_ashr_i32 s21, s20, 31
	v_ashrrev_i32_e32 v3, 31, v30
	v_lshrrev_b32_e32 v4, 4, v2
	s_lshl_b64 s[0:1], s[20:21], 19
	v_lshrrev_b32_e32 v3, 26, v3
	v_bitop3_b32 v2, v4, v2, 32 bitop3:0x6c
	s_add_u32 s0, s12, s0
	v_add_u32_e32 v3, v30, v3
	v_ashrrev_i32_e32 v5, 31, v2
	s_addc_u32 s1, s13, s1
	v_ashrrev_i32_e32 v3, 6, v3
	v_lshrrev_b32_e32 v5, 26, v5
	s_add_u32 s0, s0, s3
	v_lshlrev_b32_e32 v4, 3, v3
	v_add_u32_e32 v5, v2, v5
	s_addc_u32 s1, s1, 0
	v_and_b32_e32 v4, -16, v4
	v_ashrrev_i32_e32 v6, 6, v5
	v_and_b32_e32 v5, 0xc0, v5
	s_add_u32 s8, s0, 0x2559000
	v_readfirstlane_b32 s0, v30
	v_add_u32_e32 v4, v6, v4
	v_sub_u32_e32 v2, v2, v5
	v_mov_b32_e32 v5, 1
	s_addc_u32 s9, s1, 0
	s_ashr_i32 s6, s0, 6
	v_lshlrev_b32_e32 v3, 5, v3
	v_ashrrev_i16_sdwa v2, v5, sext(v2) dst_sel:DWORD dst_unused:UNUSED_PAD src0_sel:DWORD src1_sel:BYTE_0
	v_lshlrev_b32_e32 v5, 1, v4
	v_lshrrev_b32_e32 v7, 2, v4
	v_and_b32_e32 v6, 3, v6
	s_mov_b32 s1, 0x1fffe0
	v_and_b32_e32 v3, 32, v3
	v_bfe_i32 v2, v2, 0, 16
	v_and_b32_e32 v5, 24, v5
	v_and_b32_e32 v7, 4, v7
	v_and_or_b32 v6, v4, s1, v6
	s_lshl_b32 s25, s6, 10
	v_or3_b32 v5, v6, v7, v5
	v_add_lshl_u32 v3, v3, v2, 1
	s_add_i32 s23, s25, 0
	v_lshl_add_u32 v2, v4, 11, v3
	v_lshl_add_u32 v4, v5, 11, v3
	v_mov_b32_e32 v5, 0
	s_add_i32 m0, s23, 0x10000
	v_lshl_add_u64 v[26:27], s[8:9], 0, v[4:5]
	global_load_lds_dwordx4 v4, s[8:9]
	s_mov_b64 s[8:9], 0x20000
	v_lshl_add_u64 v[28:29], v[26:27], 0, s[8:9]
	s_add_i32 m0, s23, 0x12000
	v_mov_b32_e32 v3, v5
	global_load_lds_dwordx4 v[28:29], off
	v_lshl_add_u64 v[22:23], s[4:5], 0, v[2:3]
	s_mov_b32 m0, s23
	s_add_i32 s24, s23, 0x2000
	global_load_lds_dwordx4 v2, s[4:5]
	v_lshl_add_u64 v[24:25], v[22:23], 0, s[8:9]
	s_mov_b32 m0, s24
	s_mov_b64 s[4:5], 0x40000
	global_load_lds_dwordx4 v[24:25], off
	v_lshl_add_u64 v[18:19], v[26:27], 0, s[4:5]
	s_add_i32 m0, s23, 0x14000
	s_mov_b64 s[8:9], 0x60000
	global_load_lds_dwordx4 v[18:19], off
	v_lshl_add_u64 v[20:21], v[26:27], 0, s[8:9]
	s_add_i32 m0, s23, 0x16000
	s_add_i32 s14, s23, 0x4000
	global_load_lds_dwordx4 v[20:21], off
	v_lshl_add_u64 v[8:9], v[22:23], 0, s[4:5]
	s_mov_b32 m0, s14
	s_add_i32 s21, s23, 0x6000
	global_load_lds_dwordx4 v[8:9], off
	v_lshl_add_u64 v[14:15], v[22:23], 0, s[8:9]
	s_mov_b32 m0, s21
	s_ashr_i32 s3, s0, 8
	global_load_lds_dwordx4 v[14:15], off
	s_cmp_lg_u32 s3, 1
	s_cbranch_scc1 .LBB0_1128
	s_barrier
